# speedup vs baseline: 1.0010x; 1.0010x over previous
;   __device__ __forceinline__ const h16* gptr(int mv, int k) const {
;     int mt = mv >> 7, r = mv & 127, b = mt / 33, s = (mt - b * 33) * 126 + r - 1;
;     if (s >= 0 && s < S_) return xh + ((size_t)(b * S_ + s)) * 1024 + k;
;     return zero;
;   }
;   __device__ __forceinline__ Raw fetch(int mv, int k) const {
;     int mt = mv >> 7, r = mv & 127, b = mt / 33, s = (mt - b * 33) * 126 + r - 1;
;     if (s >= 0 && s < S_) return *(const h8*)(xh + ((size_t)(b * S_ + s)) * 1024 + k);
;     return zero8();
;   }
; template <bool DRY, class AL, class BL, class EP>
; __device__ __forceinline__ void gemm_(int MT, int NT, int K, const AL& al, const BL& bl, const EP& ep, char* smem, int& rot) {
;     ...
;   for (int t = first; t < ntiles; t += G) {
;     int mt, nt;
;     if (mfast) {
;       int grp = t / (GM * NT), rr = t - grp * (GM * NT);
;       int gm = MT - grp * GM; if (gm > GM) gm = GM;
;       nt = rr / gm; mt = grp * GM + (rr - nt * gm);
;     } else {
;       int grp = t / (GM * MT), rr = t - grp * (GM * MT);
;       int gn = NT - grp * GM; if (gn > GM) gn = GM;
;       mt = rr / gn; nt = grp * GM + (rr - mt * gn);
;     }
;     f16v acc[2][2];
; #pragma unroll
;     for (int i = 0; i < 2; ++i)
; #pragma unroll
;       for (int j = 0; j < 2; ++j)
; #pragma unroll
;         for (int r = 0; r < 16; ++r) acc[i][j][r] = 0.f;
;     const int am = mt * 128, bn = nt * 128;
;     typename AL::Raw ra[4];
;     typename BL::Raw rb[4];
.LBB0_1412:
	s_mul_hi_i32 s0, s17, 0x2e8ba2e9
	s_lshr_b32 s1, s0, 31
	s_ashr_i32 s0, s0, 9
	s_add_i32 s0, s0, s1
	s_lshl_b32 s1, s0, 6
	s_sub_i32 s2, 0x84, s1
	s_min_u32 s2, s2, 64
	v_cvt_f32_ubyte0_e32 v2, s2
	v_rcp_iflag_f32_e32 v2, v2
	s_sub_i32 s10, 0, s2
	s_mulk_i32 s0, 0xf500
	s_add_i32 s0, s0, s17
	v_mul_f32_e32 v2, 0x4f7ffffe, v2
	v_cvt_u32_f32_e32 v2, v2
	s_abs_i32 s9, s0
	s_ashr_i32 s8, s0, 31
	s_mov_b32 s3, 0x3e0f83e1
	v_readfirstlane_b32 s11, v2
	s_mul_i32 s10, s10, s11
	s_mul_hi_u32 s10, s11, s10
	s_add_i32 s11, s11, s10
	s_mul_hi_u32 s10, s9, s11
	s_mul_i32 s11, s10, s2
	s_sub_i32 s9, s9, s11
	s_add_i32 s11, s10, 1
	s_sub_i32 s12, s9, s2
	s_cmp_ge_u32 s9, s2
	s_cselect_b32 s10, s11, s10
	s_cselect_b32 s9, s12, s9
	s_add_i32 s11, s10, 1
	s_cmp_ge_u32 s9, s2
	s_cselect_b32 s9, s11, s10
	s_xor_b32 s9, s9, s8
	s_sub_i32 s40, s9, s8
	s_mul_i32 s2, s2, s40
	s_sub_i32 s2, s0, s2
	s_add_i32 s2, s2, s1
	s_lshl_b32 s0, s2, 7
	v_add_u32_e32 v2, s0, v110
	v_ashrrev_i32_e32 v2, 7, v2
	v_mul_hi_i32 v3, v2, s3
	v_lshrrev_b32_e32 v4, 31, v3
	v_ashrrev_i32_e32 v3, 3, v3
	v_add_u32_e32 v3, v3, v4
	s_movk_i32 s14, 0xffdf
	v_mad_i32_i24 v2, v3, s14, v2
	s_movk_i32 s15, 0x7e
	v_mul_lo_u32 v12, v2, s15
	v_add_u32_e32 v4, v111, v12
	v_lshlrev_b32_e32 v13, 12, v3
	v_add_u32_e32 v2, v4, v13
	v_ashrrev_i32_e32 v3, 31, v2
	v_lshlrev_b64 v[2:3], 11, v[2:3]
	v_lshl_add_u64 v[2:3], v[66:67], 0, v[2:3]
	v_mov_b32_e32 v5, s27
	v_cmp_gt_u32_e64 s[8:9], s65, v4
	v_mov_b32_e32 v4, s22
	v_readfirstlane_b32 s1, v112
	v_cndmask_b32_e64 v3, v5, v3, s[8:9]
	v_cndmask_b32_e64 v2, v4, v2, s[8:9]
	s_mov_b32 m0, s1
	v_readfirstlane_b32 s1, v115
	global_load_lds_dwordx4 v[2:3], off
	v_add_u32_e32 v2, s0, v113
	v_ashrrev_i32_e32 v2, 7, v2
	v_mul_hi_i32 v3, v2, s3
	v_lshrrev_b32_e32 v6, 31, v3
	v_ashrrev_i32_e32 v3, 3, v3
	v_add_u32_e32 v3, v3, v6
	v_mad_i32_i24 v2, v3, s14, v2
	v_mul_lo_u32 v14, v2, s15
	v_add_u32_e32 v6, v114, v14
	v_lshlrev_b32_e32 v15, 12, v3
	v_add_u32_e32 v2, v6, v15
	v_ashrrev_i32_e32 v3, 31, v2
	v_lshlrev_b64 v[2:3], 11, v[2:3]
	v_lshl_add_u64 v[2:3], v[66:67], 0, v[2:3]
	v_cmp_gt_u32_e64 s[10:11], s65, v6
	s_mov_b32 m0, s1
	v_readfirstlane_b32 s1, v118
	v_cndmask_b32_e64 v3, v5, v3, s[10:11]
	v_cndmask_b32_e64 v2, v4, v2, s[10:11]
	global_load_lds_dwordx4 v[2:3], off
	v_add_u32_e32 v2, s0, v116
	v_ashrrev_i32_e32 v2, 7, v2
	v_mul_hi_i32 v3, v2, s3
	v_lshrrev_b32_e32 v6, 31, v3
	v_ashrrev_i32_e32 v3, 3, v3
	v_add_u32_e32 v3, v3, v6
	v_mad_i32_i24 v2, v3, s14, v2
	v_mul_lo_u32 v16, v2, s15
	v_add_u32_e32 v6, v117, v16
	v_lshlrev_b32_e32 v17, 12, v3
	v_add_u32_e32 v2, v6, v17
	v_ashrrev_i32_e32 v3, 31, v2
	v_lshlrev_b64 v[2:3], 11, v[2:3]
	v_lshl_add_u64 v[2:3], v[66:67], 0, v[2:3]
	v_cmp_gt_u32_e64 s[12:13], s65, v6
	s_mov_b32 m0, s1
	v_add_u32_e32 v126, 0x8000, v112
	v_cndmask_b32_e64 v3, v5, v3, s[12:13]
	v_cndmask_b32_e64 v2, v4, v2, s[12:13]
	global_load_lds_dwordx4 v[2:3], off
	v_add_u32_e32 v2, s0, v119
	v_ashrrev_i32_e32 v2, 7, v2
	v_mul_hi_i32 v3, v2, s3
	v_lshrrev_b32_e32 v6, 31, v3
	v_ashrrev_i32_e32 v3, 3, v3
	v_add_u32_e32 v3, v3, v6
	v_mad_i32_i24 v2, v3, s14, v2
	v_mul_lo_u32 v18, v2, s15
	v_add_u32_e32 v6, v120, v18
	v_lshlrev_b32_e32 v19, 12, v3
	v_add_u32_e32 v2, v6, v19
	v_ashrrev_i32_e32 v3, 31, v2
	v_lshlrev_b64 v[2:3], 11, v[2:3]
	v_lshl_add_u64 v[2:3], v[66:67], 0, v[2:3]
	v_cmp_gt_u32_e64 s[14:15], s65, v6
	v_readfirstlane_b32 s0, v121
	s_mov_b32 m0, s0
	v_cndmask_b32_e64 v3, v5, v3, s[14:15]
	v_cndmask_b32_e64 v2, v4, v2, s[14:15]
	s_lshl_b32 s0, s40, 7
	global_load_lds_dwordx4 v[2:3], off
	v_add_u32_e32 v2, s0, v110
	v_ashrrev_i32_e32 v2, 1, v2
	v_and_or_b32 v2, v2, s19, v122
	v_add_u32_e32 v3, 0xb00, v2
	v_cndmask_b32_e64 v2, v3, v2, s[4:5]
	v_ashrrev_i32_e32 v3, 31, v2
	v_lshlrev_b64 v[2:3], 11, v[2:3]
	v_readfirstlane_b32 s1, v126
	v_lshl_add_u64 v[4:5], v[68:69], 0, v[2:3]
	s_mov_b32 m0, s1
	v_add_u32_e32 v127, 0x8000, v115
	global_load_lds_dwordx4 v[4:5], off
	v_add_u32_e32 v4, s0, v113
	v_ashrrev_i32_e32 v4, 1, v4
	v_and_or_b32 v4, v4, s19, v123
	v_add_u32_e32 v5, 0xb00, v4
	v_cndmask_b32_e64 v4, v4, v5, s[4:5]
	v_ashrrev_i32_e32 v5, 31, v4
	v_lshlrev_b64 v[4:5], 11, v[4:5]
	v_readfirstlane_b32 s1, v127
	v_lshl_add_u64 v[6:7], v[68:69], 0, v[4:5]
	s_mov_b32 m0, s1
	v_add_u32_e32 v128, 0x8000, v118
	global_load_lds_dwordx4 v[6:7], off
	v_add_u32_e32 v6, s0, v116
	v_ashrrev_i32_e32 v6, 1, v6
	v_and_or_b32 v6, v6, s19, v124
	v_add_u32_e32 v7, 0xb00, v6
	v_cndmask_b32_e64 v6, v7, v6, s[4:5]
	v_ashrrev_i32_e32 v7, 31, v6
	v_lshlrev_b64 v[6:7], 11, v[6:7]
	v_readfirstlane_b32 s1, v128
	v_lshl_add_u64 v[8:9], v[68:69], 0, v[6:7]
	s_mov_b32 m0, s1
	v_add_u32_e32 v129, 0x8000, v121
	global_load_lds_dwordx4 v[8:9], off
	v_add_u32_e32 v8, s0, v119
	v_ashrrev_i32_e32 v8, 1, v8
	v_and_or_b32 v8, v8, s19, v125
	v_add_u32_e32 v9, 0xb00, v8
	v_cndmask_b32_e64 v8, v9, v8, s[6:7]
	v_ashrrev_i32_e32 v9, 31, v8
	v_lshlrev_b64 v[8:9], 11, v[8:9]
	v_readfirstlane_b32 s0, v129
	v_lshl_add_u64 v[10:11], v[68:69], 0, v[8:9]
	s_mov_b32 m0, s0
	v_readlane_b32 s0, v247, 48
	global_load_lds_dwordx4 v[10:11], off
	v_add3_u32 v10, v111, v13, v12
	v_ashrrev_i32_e32 v11, 31, v10
	v_lshlrev_b64 v[10:11], 11, v[10:11]
	v_readlane_b32 s1, v247, 49
	s_waitcnt vmcnt(0)
; template <bool DRY, class AL, class BL, class EP>
; __device__ __forceinline__ void gemm_(int MT, int NT, int K, const AL& al, const BL& bl, const EP& ep, char* smem, int& rot) {
;     ...
;     f16v acc[2][2];
; #pragma unroll
;     for (int i = 0; i < 2; ++i)
; #pragma unroll
;       for (int j = 0; j < 2; ++j)
; #pragma unroll
;         for (int r = 0; r < 16; ++r) acc[i][j][r] = 0.f;
;     const int am = mt * 128, bn = nt * 128;
;     typename AL::Raw ra[4];
;     typename BL::Raw rb[4];
;     ...
;     G_ISSUE(0, 0);
;     G_STORE(0, 0);
;     asm volatile("s_waitcnt vmcnt(0)" ::: "memory");
;     __syncthreads();
	v_lshl_add_u64 v[78:79], s[58:59], 0, v[2:3]
	v_mov_b32_e32 v2, 0
	s_waitcnt vmcnt(0)
	v_lshl_add_u64 v[70:71], s[0:1], 0, v[10:11]
	v_add3_u32 v10, v114, v15, v14
	v_ashrrev_i32_e32 v11, 31, v10
	v_lshlrev_b64 v[10:11], 11, v[10:11]
	v_lshl_add_u64 v[72:73], s[0:1], 0, v[10:11]
	v_add3_u32 v10, v117, v17, v16
	v_ashrrev_i32_e32 v11, 31, v10
	v_lshlrev_b64 v[10:11], 11, v[10:11]
	v_lshl_add_u64 v[74:75], s[0:1], 0, v[10:11]
	v_add3_u32 v10, v120, v19, v18
	v_ashrrev_i32_e32 v11, 31, v10
	v_lshlrev_b64 v[10:11], 11, v[10:11]
	s_mov_b32 s33, 0
	v_lshl_add_u64 v[76:77], s[0:1], 0, v[10:11]
	v_lshl_add_u64 v[80:81], s[58:59], 0, v[4:5]
	v_lshl_add_u64 v[82:83], s[58:59], 0, v[6:7]
	v_lshl_add_u64 v[84:85], s[58:59], 0, v[8:9]
	v_mov_b32_e32 v3, v2
	v_mov_b32_e32 v4, v2
	v_mov_b32_e32 v5, v2
	v_mov_b32_e32 v6, v2
	v_mov_b32_e32 v7, v2
	v_mov_b32_e32 v8, v2
	v_mov_b32_e32 v9, v2
	v_mov_b32_e32 v10, v2
	v_mov_b32_e32 v11, v2
	v_mov_b32_e32 v12, v2
	v_mov_b32_e32 v13, v2
	v_mov_b32_e32 v14, v2
	v_mov_b32_e32 v15, v2
	v_mov_b32_e32 v16, v2
	v_mov_b32_e32 v17, v2
	v_mov_b32_e32 v18, v2
	v_mov_b32_e32 v19, v2
	v_mov_b32_e32 v20, v2
	v_mov_b32_e32 v21, v2
	v_mov_b32_e32 v22, v2
	v_mov_b32_e32 v23, v2
	v_mov_b32_e32 v24, v2
	v_mov_b32_e32 v25, v2
	v_mov_b32_e32 v26, v2
	v_mov_b32_e32 v27, v2
	v_mov_b32_e32 v28, v2
	v_mov_b32_e32 v29, v2
	v_mov_b32_e32 v30, v2
	v_mov_b32_e32 v31, v2
	v_mov_b32_e32 v32, v2
	v_mov_b32_e32 v33, v2
	v_mov_b32_e32 v34, v2
	v_mov_b32_e32 v35, v2
	v_mov_b32_e32 v36, v2
	v_mov_b32_e32 v37, v2
	v_mov_b32_e32 v38, v2
	v_mov_b32_e32 v39, v2
	s_waitcnt vmcnt(0)
	v_mov_b32_e32 v40, v2
	v_mov_b32_e32 v41, v2
	v_mov_b32_e32 v42, v2
	v_mov_b32_e32 v43, v2
	v_mov_b32_e32 v44, v2
	v_mov_b32_e32 v45, v2
	v_mov_b32_e32 v46, v2
	v_mov_b32_e32 v47, v2
	v_mov_b32_e32 v48, v2
	v_mov_b32_e32 v49, v2
	v_mov_b32_e32 v50, v2
	v_mov_b32_e32 v51, v2
	v_mov_b32_e32 v52, v2
	v_mov_b32_e32 v53, v2
	v_mov_b32_e32 v54, v2
	v_mov_b32_e32 v55, v2
	v_mov_b32_e32 v56, v2
	v_mov_b32_e32 v57, v2
	v_mov_b32_e32 v58, v2
	v_mov_b32_e32 v59, v2
	v_mov_b32_e32 v60, v2
	v_mov_b32_e32 v61, v2
	v_mov_b32_e32 v62, v2
	v_mov_b32_e32 v63, v2
	v_mov_b32_e32 v64, v2
	v_mov_b32_e32 v65, v2
	s_waitcnt lgkmcnt(0)
	s_barrier
	v_lshl_add_u64 v[70:71], v[70:71], 0, v[0:1]
	v_lshl_add_u64 v[72:73], v[72:73], 0, v[0:1]
	v_lshl_add_u64 v[74:75], v[74:75], 0, v[0:1]
	v_lshl_add_u64 v[76:77], v[76:77], 0, v[0:1]
	v_lshl_add_u64 v[78:79], v[78:79], 0, v[0:1]
	v_lshl_add_u64 v[80:81], v[80:81], 0, v[0:1]
	v_lshl_add_u64 v[82:83], v[82:83], 0, v[0:1]
	v_lshl_add_u64 v[84:85], v[84:85], 0, v[0:1]
	s_branch .LBB0_1414

; template <bool DRY, class AL, class BL, class EP>
; __device__ __forceinline__ void gemm_(int MT, int NT, int K, const AL& al, const BL& bl, const EP& ep, char* smem, int& rot) {
;     ...
;     G_ISSUE(0, 0);
;     G_STORE(0, 0);
;     asm volatile("s_waitcnt vmcnt(0)" ::: "memory");
;     __syncthreads();
;     for (int kt = 0; kt < KT; kt += 2) {
;       if (kt + 1 < KT) G_ISSUE(1, (kt + 1) * 64);
;       G_COMPUTE(0);
;       if (kt + 1 < KT) G_STORE(1, (kt + 1) * 64);
;       asm volatile("s_waitcnt vmcnt(0)" ::: "memory");
;       __syncthreads();
;       if (kt + 1 >= KT) break;
;       if (kt + 2 < KT) G_ISSUE(0, (kt + 2) * 64);
;       G_COMPUTE(1);
;       if (kt + 2 < KT) G_STORE(0, (kt + 2) * 64);
;       asm volatile("s_waitcnt vmcnt(0)" ::: "memory");
;       __syncthreads();
;     }
.LBB0_1414:
	s_mov_b64 s[46:47], 0x80
	v_add_u32_e32 v90, 0x4000, v112
	v_lshl_add_u64 v[88:89], v[70:71], 0, s[46:47]
	v_mov_b32_e32 v96, s27
	v_mov_b32_e32 v97, s22
	v_readfirstlane_b32 s0, v90
	v_cndmask_b32_e64 v89, v96, v89, s[8:9]
	v_cndmask_b32_e64 v88, v97, v88, s[8:9]
	s_mov_b32 m0, s0
	v_add_u32_e32 v92, 0x4000, v115
	global_load_lds_dwordx4 v[88:89], off
	v_lshl_add_u64 v[90:91], v[72:73], 0, s[46:47]
	v_readfirstlane_b32 s0, v92
	v_cndmask_b32_e64 v91, v96, v91, s[10:11]
	v_cndmask_b32_e64 v90, v97, v90, s[10:11]
	s_mov_b32 m0, s0
	v_add_u32_e32 v94, 0x4000, v118
	global_load_lds_dwordx4 v[90:91], off
	v_lshl_add_u64 v[92:93], v[74:75], 0, s[46:47]
	v_readfirstlane_b32 s0, v94
	v_cndmask_b32_e64 v93, v96, v93, s[12:13]
	v_cndmask_b32_e64 v92, v97, v92, s[12:13]
	s_mov_b32 m0, s0
	v_add_u32_e32 v98, 0xc000, v112
	global_load_lds_dwordx4 v[92:93], off
	v_lshl_add_u64 v[94:95], v[76:77], 0, s[46:47]
	v_cndmask_b32_e64 v95, v96, v95, s[14:15]
	v_add_u32_e32 v96, 0x4000, v121
	v_cndmask_b32_e64 v94, v97, v94, s[14:15]
	v_readfirstlane_b32 s0, v96
	s_mov_b32 m0, s0
	s_mov_b64 s[46:47], 0x4e80080
	global_load_lds_dwordx4 v[94:95], off
	v_readfirstlane_b32 s0, v98
	v_lshl_add_u64 v[96:97], v[78:79], 0, s[46:47]
	s_mov_b32 m0, s0
	v_add_u32_e32 v100, 0xc000, v115
	global_load_lds_dwordx4 v[96:97], off
	v_readfirstlane_b32 s0, v100
	v_lshl_add_u64 v[98:99], v[80:81], 0, s[46:47]
	s_mov_b32 m0, s0
	v_add_u32_e32 v130, 0xc000, v118
	global_load_lds_dwordx4 v[98:99], off
	v_readfirstlane_b32 s0, v130
	v_lshl_add_u64 v[100:101], v[82:83], 0, s[46:47]
	s_mov_b32 m0, s0
	v_add_u32_e32 v132, 0xc000, v121
	global_load_lds_dwordx4 v[100:101], off
	v_readfirstlane_b32 s0, v132
	v_lshl_add_u64 v[130:131], v[84:85], 0, s[46:47]
	s_mov_b32 m0, s0
	s_cmp_gt_u32 s33, 13
	global_load_lds_dwordx4 v[130:131], off
	ds_read_b128 v[130:133], v102 offset:0
	ds_read_b128 v[134:137], v102 offset:0x1000
	ds_read_b128 v[138:141], v103 offset:0x8000
	ds_read_b128 v[142:145], v103 offset:0x9000
	s_cselect_b64 s[0:1], -1, 0
	s_waitcnt lgkmcnt(0)
	s_and_b64 vcc, exec, s[0:1]
	v_mfma_f32_32x32x16_f16 v[50:65], v[130:133], v[138:141], v[50:65]
	v_mfma_f32_32x32x16_f16 v[34:49], v[130:133], v[142:145], v[34:49]
	ds_read_b128 v[130:133], v104 offset:0
	v_mfma_f32_32x32x16_f16 v[18:33], v[134:137], v[138:141], v[18:33]
	v_mfma_f32_32x32x16_f16 v[2:17], v[134:137], v[142:145], v[2:17]
	ds_read_b128 v[134:137], v104 offset:0x1000
	ds_read_b128 v[138:141], v105 offset:0x8000
	ds_read_b128 v[142:145], v105 offset:0x9000
	s_nop 0
	s_waitcnt lgkmcnt(0)
	s_nop 0
	v_mfma_f32_32x32x16_f16 v[50:65], v[130:133], v[138:141], v[50:65]
	v_mfma_f32_32x32x16_f16 v[34:49], v[130:133], v[142:145], v[34:49]
	ds_read_b128 v[130:133], v106 offset:0
	v_mfma_f32_32x32x16_f16 v[18:33], v[134:137], v[138:141], v[18:33]
	v_mfma_f32_32x32x16_f16 v[2:17], v[134:137], v[142:145], v[2:17]
	ds_read_b128 v[134:137], v106 offset:0x1000
	ds_read_b128 v[138:141], v107 offset:0x8000
	ds_read_b128 v[142:145], v107 offset:0x9000
	s_nop 0
	s_waitcnt lgkmcnt(0)
	s_nop 0
	v_mfma_f32_32x32x16_f16 v[50:65], v[130:133], v[138:141], v[50:65]
	v_mfma_f32_32x32x16_f16 v[34:49], v[130:133], v[142:145], v[34:49]
	ds_read_b128 v[130:133], v108 offset:0
	v_mfma_f32_32x32x16_f16 v[18:33], v[134:137], v[138:141], v[18:33]
	v_mfma_f32_32x32x16_f16 v[2:17], v[134:137], v[142:145], v[2:17]
	ds_read_b128 v[134:137], v108 offset:0x1000
	ds_read_b128 v[138:141], v109 offset:0x8000
	ds_read_b128 v[142:145], v109 offset:0x9000
	s_nop 0
	s_waitcnt lgkmcnt(0)
	s_waitcnt vmcnt(0)
	s_waitcnt vmcnt(0) lgkmcnt(0)
	v_mfma_f32_32x32x16_f16 v[50:65], v[130:133], v[138:141], v[50:65]
	s_barrier
	v_mfma_f32_32x32x16_f16 v[34:49], v[130:133], v[142:145], v[34:49]
	v_mfma_f32_32x32x16_f16 v[18:33], v[134:137], v[138:141], v[18:33]
	v_mfma_f32_32x32x16_f16 v[2:17], v[134:137], v[142:145], v[2:17]
	s_cbranch_vccnz .LBB0_1413
	v_lshl_add_u64 v[86:87], v[70:71], 0, s[70:71]
	v_mov_b32_e32 v130, s27
	v_mov_b32_e32 v131, s22
	v_readfirstlane_b32 s41, v112
	v_cndmask_b32_e64 v87, v130, v87, s[8:9]
	v_cndmask_b32_e64 v86, v131, v86, s[8:9]
	s_mov_b32 m0, s41
	v_readfirstlane_b32 s41, v115
	global_load_lds_dwordx4 v[86:87], off
	v_lshl_add_u64 v[86:87], v[72:73], 0, s[70:71]
	v_cndmask_b32_e64 v87, v130, v87, s[10:11]
	v_cndmask_b32_e64 v86, v131, v86, s[10:11]
	s_mov_b32 m0, s41
	v_readfirstlane_b32 s41, v118
	global_load_lds_dwordx4 v[86:87], off
	v_lshl_add_u64 v[86:87], v[74:75], 0, s[70:71]
	v_cndmask_b32_e64 v87, v130, v87, s[12:13]
	v_cndmask_b32_e64 v86, v131, v86, s[12:13]
	s_mov_b32 m0, s41
	v_readfirstlane_b32 s41, v121
	global_load_lds_dwordx4 v[86:87], off
	v_lshl_add_u64 v[86:87], v[76:77], 0, s[70:71]
	v_cndmask_b32_e64 v87, v130, v87, s[14:15]
	v_cndmask_b32_e64 v86, v131, v86, s[14:15]
	s_mov_b32 m0, s41
	s_mov_b64 s[46:47], 0x4e80100
	v_readfirstlane_b32 s41, v126
	global_load_lds_dwordx4 v[86:87], off
	v_lshl_add_u64 v[86:87], v[78:79], 0, s[46:47]
	s_mov_b32 m0, s41
	v_readfirstlane_b32 s41, v127
	global_load_lds_dwordx4 v[86:87], off
	v_lshl_add_u64 v[86:87], v[80:81], 0, s[46:47]
	s_mov_b32 m0, s41
	v_readfirstlane_b32 s41, v128
	global_load_lds_dwordx4 v[86:87], off
	v_lshl_add_u64 v[86:87], v[82:83], 0, s[46:47]
	s_mov_b32 m0, s41
	v_readfirstlane_b32 s41, v129
	global_load_lds_dwordx4 v[86:87], off
	v_lshl_add_u64 v[86:87], v[84:85], 0, s[46:47]
	s_mov_b32 m0, s41
	s_nop 0
	global_load_lds_dwordx4 v[86:87], off
	s_branch .LBB0_1413
